# first_seam_xcd_barrier_instead_of_cg_grid_sync
# speedup vs baseline: 1.0085x; 1.0085x over previous
.LBB0_378:
	v_readlane_b32 s0, v253, 4
	s_cmp_eq_u32 s0, 1
	s_cbranch_scc1 .LBB0_390
	s_waitcnt vmcnt(0)
	s_waitcnt vmcnt(0) lgkmcnt(0)
	s_barrier
	s_mov_b64 s[4:5], exec
	v_readlane_b32 s0, v253, 2
	v_readlane_b32 s1, v253, 3
	s_and_b64 s[0:1], s[4:5], s[0:1]
	s_mov_b64 exec, s[0:1]
	s_cbranch_execz .Lxb0_465
	s_add_i32 s0, 0, 0x23ff0
	v_mov_b32_e32 v0, s0
	s_waitcnt vmcnt(0) expcnt(0) lgkmcnt(0)
	ds_read_b32 v2, v0
	s_add_i32 s0, 0, 0x23ff4
	v_mov_b32_e32 v0, s0
	ds_read_b32 v0, v0
	s_waitcnt lgkmcnt(1)
	v_cmp_ne_u32_e32 vcc, 0, v2
	s_cbranch_vccnz .Lxb0_430
	v_readlane_b32 s6, v253, 0
	v_readlane_b32 s7, v253, 1
	s_load_dwordx2 s[0:1], s[6:7], 0x4
	s_add_u32 s6, s70, 0x1000
	s_addc_u32 s7, s71, 0
	s_add_u32 s8, s70, 0x1100
	s_addc_u32 s9, s71, 0
	s_add_u32 s10, s70, 0x1200
	s_addc_u32 s11, s71, 0
	s_waitcnt lgkmcnt(0)
	s_mul_i32 s18, s0, s90
	s_add_u32 s12, s70, 0x1300
	s_mul_i32 s18, s18, s1
	s_addc_u32 s13, s71, 0
	s_mov_b32 s19, 1
	v_mov_b32_e32 v16, 0
	s_branch .Lxb0_418

.Lxb0_430:
	s_mov_b64 s[0:1], exec
	v_readlane_b32 s6, v253, 5
	s_lshl_b32 s6, s6, 8
	v_mbcnt_lo_u32_b32 v1, s0, 0
	s_add_u32 s6, s70, s6
	v_mbcnt_hi_u32_b32 v1, s1, v1
	s_addc_u32 s7, s71, 0
	v_cmp_eq_u32_e32 vcc, 0, v1

	s_and_saveexec_b64 s[8:9], vcc
	s_cbranch_execz .Lxb0_432
	s_bcnt1_i32_b64 s0, s[0:1]
	v_mov_b32_e32 v3, 0x1000
	v_mov_b32_e32 v4, s0
	global_atomic_add v3, v3, v4, s[6:7] offset:1024 sc0
.Lxb0_432:
	s_or_b64 exec, exec, s[8:9]
	v_cvt_f32_u32_e32 v4, v2
	s_waitcnt vmcnt(0)
	v_readfirstlane_b32 s0, v3
	v_sub_u32_e32 v3, 0, v2
	v_rcp_iflag_f32_e32 v4, v4
	v_add_u32_e32 v5, s0, v1
	v_mul_f32_e32 v4, 0x4f7ffffe, v4
	v_cvt_u32_f32_e32 v4, v4
	v_mul_lo_u32 v1, v3, v4
	v_mul_hi_u32 v1, v4, v1
	v_add_u32_e32 v1, v4, v1
	v_mul_hi_u32 v1, v5, v1
	v_mul_lo_u32 v3, v1, v2
	v_sub_u32_e32 v3, v5, v3
	v_add_u32_e32 v4, 1, v1
	v_cmp_ge_u32_e32 vcc, v3, v2
	s_nop 1
	v_cndmask_b32_e32 v1, v1, v4, vcc
	v_sub_u32_e32 v4, v3, v2
	v_cndmask_b32_e32 v3, v3, v4, vcc
	v_add_u32_e32 v4, 1, v1
	v_cmp_ge_u32_e32 vcc, v3, v2
	v_add_u32_e32 v3, 1, v5
	s_nop 0
	v_cndmask_b32_e32 v1, v1, v4, vcc
	v_mul_lo_u32 v4, v2, v1
	v_add_u32_e32 v2, v4, v2
	v_cmp_ne_u32_e32 vcc, v3, v2
	s_and_saveexec_b64 s[0:1], vcc
	s_xor_b64 s[8:9], exec, s[0:1]
	s_cbranch_execz .Lxb0_446
	s_waitcnt lgkmcnt(0)
	v_mov_b32_e32 v0, 0x2000
	global_load_dword v0, v0, s[6:7] offset:1024 sc1
	s_add_u32 s12, s6, 0x2400
	s_addc_u32 s13, s7, 0
	s_waitcnt vmcnt(0)
	v_cmp_eq_u32_e32 vcc, v0, v1
	s_and_saveexec_b64 s[10:11], vcc
	s_cbranch_execz .Lxb0_445
	s_mov_b32 s22, 1
	s_mov_b64 s[14:15], 0
	v_mov_b32_e32 v0, 0

	s_branch .Lxb0_436

.Lxb0_436:
	s_and_b32 s0, s22, 0xff
	s_mov_b64 s[18:19], -1
	s_cmp_lg_u32 s0, 0
	s_mov_b64 s[0:1], -1
	s_sleep 1

	s_cbranch_scc1 .Lxb0_439
	global_load_dword v2, v0, s[70:71] offset:512 sc1
	s_waitcnt vmcnt(0)
	v_cmp_eq_u32_e32 vcc, 0, v2
	s_cbranch_vccnz .Lxb0_441
	s_mov_b64 s[0:1], 0
	s_mov_b64 s[20:21], -1

.Lxb0_445:
	s_or_b64 exec, exec, s[10:11]
	s_waitcnt vmcnt(0)
	buffer_inv sc1
	s_waitcnt vmcnt(0)

.Lxb0_446:
	s_andn2_saveexec_b64 s[0:1], s[8:9]
	s_cbranch_execz .Lxb0_465
	s_mov_b64 s[0:1], exec
	buffer_wbl2 sc1
	s_waitcnt lgkmcnt(0)
	s_waitcnt vmcnt(0)
	v_mbcnt_lo_u32_b32 v1, s0, 0
	s_add_u32 s8, s70, 0x3400
	v_mbcnt_hi_u32_b32 v1, s1, v1
	s_addc_u32 s9, s71, 0
	v_cmp_eq_u32_e32 vcc, 0, v1

	s_and_saveexec_b64 s[10:11], vcc
	s_cbranch_execz .Lxb0_449
	s_bcnt1_i32_b64 s0, s[0:1]
	v_mov_b32_e32 v2, 0
	v_mov_b32_e32 v3, s0
	global_atomic_add v2, v2, v3, s[8:9] sc0
.Lxb0_449:
	s_or_b64 exec, exec, s[10:11]
	v_cvt_f32_u32_e32 v3, v0
	s_waitcnt vmcnt(0)
	v_readfirstlane_b32 s0, v2
	v_sub_u32_e32 v2, 0, v0
	v_rcp_iflag_f32_e32 v3, v3
	v_add_u32_e32 v1, s0, v1
	v_mul_f32_e32 v3, 0x4f7ffffe, v3
	v_cvt_u32_f32_e32 v3, v3
	v_mul_lo_u32 v2, v2, v3
	v_mul_hi_u32 v2, v3, v2
	v_add_u32_e32 v2, v3, v2
	v_mul_hi_u32 v2, v1, v2
	v_mul_lo_u32 v3, v2, v0
	v_sub_u32_e32 v3, v1, v3
	v_add_u32_e32 v4, 1, v2
	v_cmp_ge_u32_e32 vcc, v3, v0
	v_add_u32_e32 v1, 1, v1
	s_nop 0
	v_cndmask_b32_e32 v2, v2, v4, vcc
	v_sub_u32_e32 v4, v3, v0
	v_cndmask_b32_e32 v3, v3, v4, vcc
	v_add_u32_e32 v4, 1, v2
	v_cmp_ge_u32_e32 vcc, v3, v0
	s_nop 1
	v_cndmask_b32_e32 v2, v2, v4, vcc
	v_mul_lo_u32 v2, v0, v2
	v_add_u32_e32 v0, v2, v0
	v_cmp_ne_u32_e32 vcc, v1, v0
	s_and_saveexec_b64 s[10:11], vcc
	s_cbranch_execz .Lxb0_462
	v_mov_b32_e32 v1, 0
	global_load_dword v2, v1, s[8:9] sc1
	s_waitcnt vmcnt(0)
	v_cmp_lt_u32_e32 vcc, v2, v0
	s_and_b64 exec, exec, vcc
	s_cbranch_execz .Lxb0_462
	s_mov_b32 s20, 1
	s_mov_b64 s[12:13], 0

	s_branch .Lxb0_453

.Lxb0_453:
	s_and_b32 s0, s20, 0xff
	s_mov_b64 s[16:17], -1
	s_cmp_lg_u32 s0, 0
	s_mov_b64 s[0:1], -1
	s_sleep 1

	s_cbranch_scc1 .Lxb0_456
	global_load_dword v2, v1, s[70:71] offset:512 sc1
	s_waitcnt vmcnt(0)
	v_cmp_eq_u32_e32 vcc, 0, v2
	s_cbranch_vccnz .Lxb0_458
	s_mov_b64 s[0:1], 0
	s_mov_b64 s[18:19], -1

.Lxb0_465:
	s_or_b64 exec, exec, s[4:5]
	s_waitcnt lgkmcnt(0)
	s_barrier
.LBB0_390:
	v_readlane_b32 s0, v253, 4
	s_cmp_lt_i32 s0, 2
	s_cbranch_scc1 .LBB0_466
	s_cmpk_gt_i32 s2, 0x6ff
	v_readfirstlane_b32 s0, v170
	s_cbranch_scc1 .LBB0_413
	s_load_dwordx2 s[6:7], s[92:93], 0x118
	v_lshrrev_b32_e32 v0, 5, v170
	v_lshrrev_b32_e32 v2, 1, v170
	v_and_b32_e32 v0, 4, v0
	v_bfe_u32 v1, v170, 2, 2
	v_and_b32_e32 v2, 24, v2
	v_or3_b32 v0, v0, v1, v2
	v_lshlrev_b32_e32 v1, 4, v170
	v_add_u32_e32 v10, 0x2000, v1
	v_and_b32_e32 v4, 32, v170
	v_lshrrev_b32_e32 v2, 7, v10
	s_movk_i32 s4, 0xe0
	v_bitop3_b32 v8, v1, v4, 48 bitop3:0x6c
	v_and_b32_e32 v9, 64, v170
	s_waitcnt lgkmcnt(0)
	s_add_u32 s33, s6, 0x100000
	v_and_or_b32 v3, v2, s4, v0
	v_or_b32_e32 v1, v8, v9
	s_addc_u32 s40, s7, 0
	v_lshl_or_b32 v128, v3, 11, v1
	v_lshrrev_b32_e32 v3, 3, v170
	s_movk_i32 s4, 0x60
	s_add_u32 s41, s6, 0x4400000
	v_and_or_b32 v0, v3, s4, v0
	v_bfe_u32 v11, v170, 2, 4
	s_movk_i32 s4, 0xf0
	s_addc_u32 s42, s7, 0
	v_lshl_or_b32 v130, v0, 11, v1
	v_and_or_b32 v0, v2, s4, v11
	s_movk_i32 s4, 0x70
	s_ashr_i32 s44, s2, 31
	v_lshl_or_b32 v132, v0, 11, v1
	v_and_or_b32 v0, v3, s4, v11
	s_lshr_b32 s4, s44, 29
	s_add_i32 s4, s2, s4
	s_lshr_b32 s10, s0, 6
	s_ashr_i32 s5, s4, 3
	s_and_b32 s4, s4, -8
	s_lshr_b32 s1, s0, 8
	s_lshl_b32 s43, s10, 10
	s_sub_i32 s4, s2, s4
	s_cmp_lt_i32 s4, 0
	s_movk_i32 s45, 0xe1
	s_cselect_b32 s8, s45, 0xe0
	s_mul_i32 s4, s8, s4
	s_add_i32 s4, s4, s5
	s_mul_hi_i32 s5, s4, 0x92492493
	s_add_i32 s5, s5, s4
	s_lshr_b32 s8, s5, 31
	s_ashr_i32 s5, s5, 6
	s_add_i32 s5, s5, s8
	s_lshl_b32 s8, s5, 3
	s_mulk_i32 s5, 0x70
	s_sub_i32 s4, s4, s5
	s_bfe_i32 s5, s4, 0x80000
	s_bfe_u32 s5, s5, 0x3000c
	s_add_i32 s5, s4, s5
	s_bfe_i32 s9, s5, 0x80000
	s_and_b32 s5, s5, 0xf8
	s_sext_i32_i16 s9, s9
	s_sub_i32 s4, s4, s5
	s_lshr_b32 s12, s9, 3
	s_sext_i32_i8 s4, s4
	s_add_i32 s30, s8, s4
	s_bfe_i64 s[4:5], s[12:13], 0x100000
	s_lshl_b64 s[34:35], s[4:5], 19
	s_add_u32 s14, s33, s34
	s_addc_u32 s15, s40, s35
	s_add_i32 s46, s43, 0
	s_add_i32 m0, s46, 0x10000
	v_lshl_or_b32 v134, v0, 11, v1
	global_load_lds_dwordx4 v130, s[14:15]
	s_add_i32 m0, s46, 0x12000
	s_add_u32 s4, s14, 0x40000
	global_load_lds_dwordx4 v128, s[14:15]
	s_addc_u32 s5, s15, 0
	s_add_i32 m0, s46, 0x14000
	s_ashr_i32 s31, s30, 31
	global_load_lds_dwordx4 v130, s[4:5]
	s_add_i32 m0, s46, 0x16000
	v_mov_b32_e32 v131, 0
	global_load_lds_dwordx4 v128, s[4:5]
	s_lshl_b64 s[4:5], s[30:31], 19
	s_add_u32 s8, s41, s4
	s_addc_u32 s9, s42, s5
	s_add_i32 s47, s46, 0x2000
	s_mov_b32 m0, s46
	s_add_u32 s4, s8, 0x40000
	global_load_lds_dwordx4 v134, s[8:9]
	s_mov_b32 m0, s47
	s_addc_u32 s5, s9, 0
	s_add_i32 s48, s46, 0x4000
	global_load_lds_dwordx4 v132, s[8:9]
	s_mov_b32 m0, s48
	s_add_i32 s49, s46, 0x6000
	global_load_lds_dwordx4 v134, s[4:5]
	s_mov_b32 m0, s49
	v_mov_b32_e32 v129, v131
	global_load_lds_dwordx4 v132, s[4:5]
	v_mov_b32_e32 v135, v131
	v_mov_b32_e32 v133, v131
	s_cmp_eq_u32 s1, 1
	s_movk_i32 s50, 0x2000
	s_mov_b32 s62, 0
	v_lshl_add_u64 v[6:7], s[14:15], 0, v[130:131]
	v_lshl_add_u64 v[4:5], s[14:15], 0, v[128:129]
	v_lshl_add_u64 v[0:1], s[8:9], 0, v[134:135]
	s_cselect_b64 s[4:5], -1, 0
	s_cmp_lg_u32 s1, 1
	v_lshl_add_u64 v[2:3], s[8:9], 0, v[132:133]
	s_cbranch_scc1 .LBB0_394
	s_barrier
